# ret_intra QK operands fetched with coalesced loads and staged wave-locally in LDS (264-B rows) instead of row-per-lane global loads
# speedup vs baseline: 1.0049x; 1.0049x over previous
.LBB0_388:
	s_mov_b32 s4, 21
	s_ashr_i32 s5, s4, 31
	s_lshl_b64 s[4:5], s[4:5], 3
	s_add_u32 s4, s0, s4
	s_addc_u32 s5, s1, s5
	s_load_dwordx2 s[4:5], s[4:5], 0x0
	v_and_b32_e32 v226, 3, v67
	v_lshlrev_b32_e32 v0, 2, v226
	v_and_b32_e32 v18, 0xffffff80, v225
	v_or_b32_e32 v2, v182, v18
	s_waitcnt lgkmcnt(0)
	global_load_dword v22, v0, s[4:5]
	s_mov_b32 s4, 21
	s_ashr_i32 s5, s4, 31
	s_lshl_b64 s[4:5], s[4:5], 3
	s_add_u32 s4, s0, s4
	s_addc_u32 s5, s1, s5
	s_load_dwordx2 s[4:5], s[4:5], 0x0
	v_ashrrev_i32_e32 v3, 31, v2
	v_lshlrev_b64 v[2:3], 11, v[2:3]
	v_lshl_add_u64 v[2:3], s[60:61], 0, v[2:3]
	v_mov_b32_e32 v75, v1
	s_waitcnt lgkmcnt(0)
	global_load_dword v0, v0, s[4:5] offset:16
	s_movk_i32 s4, 0xffe0
	s_waitcnt vmcnt(0)
	v_mul_f32_e32 v0, 0x3fb8aa3b, v0
	v_exp_f32_e32 v19, v0
	v_lshlrev_b32_e32 v0, 9, v226
	v_lshl_add_u64 v[2:3], v[2:3], 0, v[0:1]
	v_lshl_add_u64 v[20:21], v[2:3], 0, v[74:75]
	v_and_or_b32 v2, v225, s4, v71
	v_ashrrev_i32_e32 v3, 31, v2
	v_lshlrev_b64 v[78:79], 11, v[2:3]
	v_lshl_add_u64 v[2:3], s[54:55], 0, v[78:79]
	v_lshl_add_u64 v[2:3], v[2:3], 0, v[0:1]
	v_lshl_add_u64 v[64:65], v[2:3], 0, v[74:75]
	v_and_b32_e32 v240, 63, v189
	v_lshrrev_b32_e32 v241, 4, v240
	v_and_b32_e32 v242, 15, v240
	v_and_b32_e32 v243, 31, v240
	v_lshrrev_b32_e32 v244, 5, v240
	v_lshl_add_u32 v245, v241, 3, 2
	v_sub_u32_e32 v245, v245, v243
	v_sub_u32_e32 v246, v242, v244
	v_lshlrev_b32_e32 v245, 11, v245
	v_lshl_add_u32 v246, v246, 4, v245
	v_ashrrev_i32_e32 v247, 31, v246
	s_mov_b32 s4, 0x2000
	s_mov_b32 s5, 0
	v_lshl_add_u64 v[228:229], v[20:21], 0, v[246:247]
	v_lshl_add_u64 v[232:233], v[64:65], 0, v[246:247]
	v_lshl_add_u64 v[230:231], v[228:229], 0, s[4:5]
	v_lshl_add_u64 v[234:235], v[232:233], 0, s[4:5]
	global_load_dwordx4 v[24:27], v[228:229], off offset:-4096
	global_load_dwordx4 v[28:31], v[228:229], off offset:-2048
	global_load_dwordx4 v[32:35], v[228:229], off offset:0
	global_load_dwordx4 v[36:39], v[228:229], off offset:2048
	global_load_dwordx4 v[40:43], v[230:231], off offset:-4096
	global_load_dwordx4 v[44:47], v[230:231], off offset:-2048
	global_load_dwordx4 v[48:51], v[230:231], off offset:0
	global_load_dwordx4 v[52:55], v[230:231], off offset:2048
	global_load_dwordx4 v[56:59], v[232:233], off offset:-4096
	global_load_dwordx4 v[60:63], v[232:233], off offset:-2048
	global_load_dwordx4 v[80:83], v[232:233], off offset:0
	global_load_dwordx4 v[84:87], v[232:233], off offset:2048
	global_load_dwordx4 v[88:91], v[234:235], off offset:-4096
	global_load_dwordx4 v[92:95], v[234:235], off offset:-2048
	global_load_dwordx4 v[96:99], v[234:235], off offset:0
	global_load_dwordx4 v[100:103], v[234:235], off offset:2048
	global_load_dwordx4 v[104:107], v[228:229], off offset:-3840
	global_load_dwordx4 v[108:111], v[228:229], off offset:-1792
	global_load_dwordx4 v[112:115], v[228:229], off offset:256
	global_load_dwordx4 v[116:119], v[228:229], off offset:2304
	global_load_dwordx4 v[120:123], v[230:231], off offset:-3840
	global_load_dwordx4 v[124:127], v[230:231], off offset:-1792
	global_load_dwordx4 v[128:131], v[230:231], off offset:256
	global_load_dwordx4 v[132:135], v[230:231], off offset:2304
	global_load_dwordx4 v[136:139], v[232:233], off offset:-3840
	global_load_dwordx4 v[140:143], v[232:233], off offset:-1792
	global_load_dwordx4 v[144:147], v[232:233], off offset:256
	global_load_dwordx4 v[148:151], v[232:233], off offset:2304
	global_load_dwordx4 v[152:155], v[234:235], off offset:-3840
	global_load_dwordx4 v[156:159], v[234:235], off offset:-1792
	global_load_dwordx4 v[160:163], v[234:235], off offset:256
	global_load_dwordx4 v[164:167], v[234:235], off offset:2304
	v_lshrrev_b32_e32 v248, 8, v189
	v_mul_u32_u24_e32 v248, 0x12000, v248
	v_bfe_u32 v249, v189, 6, 2
	v_mul_u32_u24_e32 v250, 0x2100, v249
	v_mul_u32_u24_e32 v168, 0x840, v241
	v_lshl_add_u32 v168, v242, 4, v168
	v_mul_u32_u24_e32 v169, 0x108, v243
	v_lshl_add_u32 v169, v244, 4, v169
	v_add_u32_e32 v251, v248, v250
	v_add_u32_e32 v251, 0x2400, v251
	v_add_u32_e32 v236, v251, v168
	v_add_u32_e32 v238, v251, v169
	v_add_u32_e32 v170, 0xa800, v250
	v_lshrrev_b32_e32 v245, 1, v241
	v_mul_u32_u24_e32 v245, 0xfa80, v245
	v_lshrrev_b32_e32 v246, 4, v243
	v_mul_u32_u24_e32 v246, 0xfa80, v246
	v_cmp_eq_u32_e64 s[10:11], 3, v249
	s_nop 3
	v_cndmask_b32_e64 v245, v170, v245, s[10:11]
	v_cndmask_b32_e64 v246, v170, v246, s[10:11]
	v_add3_u32 v237, v248, v245, v168
	v_add3_u32 v239, v248, v246, v169
	s_waitcnt vmcnt(31)
	ds_write2_b64 v236, v[24:25], v[26:27] offset0:0 offset1:1
	s_waitcnt vmcnt(30)
	ds_write2_b64 v236, v[28:29], v[30:31] offset0:33 offset1:34
	s_waitcnt vmcnt(29)
	ds_write2_b64 v236, v[32:33], v[34:35] offset0:66 offset1:67
	s_waitcnt vmcnt(28)
	ds_write2_b64 v236, v[36:37], v[38:39] offset0:99 offset1:100
	s_waitcnt vmcnt(27)
	ds_write2_b64 v236, v[40:41], v[42:43] offset0:132 offset1:133
	s_waitcnt vmcnt(26)
	ds_write2_b64 v236, v[44:45], v[46:47] offset0:165 offset1:166
	s_waitcnt vmcnt(25)
	ds_write2_b64 v236, v[48:49], v[50:51] offset0:198 offset1:199
	s_waitcnt vmcnt(24)
	ds_write2_b64 v236, v[52:53], v[54:55] offset0:231 offset1:232
	s_waitcnt vmcnt(23)
	ds_write2_b64 v237, v[56:57], v[58:59] offset0:0 offset1:1
	s_waitcnt vmcnt(22)
	ds_write2_b64 v237, v[60:61], v[62:63] offset0:33 offset1:34
	s_waitcnt vmcnt(21)
	ds_write2_b64 v237, v[80:81], v[82:83] offset0:66 offset1:67
	s_waitcnt vmcnt(20)
	ds_write2_b64 v237, v[84:85], v[86:87] offset0:99 offset1:100
	s_waitcnt vmcnt(19)
	ds_write2_b64 v237, v[88:89], v[90:91] offset0:132 offset1:133
	s_waitcnt vmcnt(18)
	ds_write2_b64 v237, v[92:93], v[94:95] offset0:165 offset1:166
	s_waitcnt vmcnt(17)
	ds_write2_b64 v237, v[96:97], v[98:99] offset0:198 offset1:199
	s_waitcnt vmcnt(16)
	ds_write2_b64 v237, v[100:101], v[102:103] offset0:231 offset1:232
	s_waitcnt lgkmcnt(0)
	ds_read2_b64 v[24:27], v238 offset0:0 offset1:1
	ds_read2_b64 v[56:59], v239 offset0:0 offset1:1
	ds_read2_b64 v[28:31], v238 offset0:4 offset1:5
	ds_read2_b64 v[60:63], v239 offset0:4 offset1:5
	ds_read2_b64 v[32:35], v238 offset0:8 offset1:9
	ds_read2_b64 v[80:83], v239 offset0:8 offset1:9
	ds_read2_b64 v[36:39], v238 offset0:12 offset1:13
	ds_read2_b64 v[84:87], v239 offset0:12 offset1:13
	ds_read2_b64 v[40:43], v238 offset0:16 offset1:17
	ds_read2_b64 v[88:91], v239 offset0:16 offset1:17
	ds_read2_b64 v[44:47], v238 offset0:20 offset1:21
	ds_read2_b64 v[92:95], v239 offset0:20 offset1:21
	ds_read2_b64 v[48:51], v238 offset0:24 offset1:25
	ds_read2_b64 v[96:99], v239 offset0:24 offset1:25
	s_waitcnt lgkmcnt(12)
	v_mfma_f32_32x32x16_bf16 v[2:17], v[24:27], v[56:59], 0
	ds_read2_b64 v[52:55], v238 offset0:28 offset1:29
	ds_read2_b64 v[100:103], v239 offset0:28 offset1:29
	s_waitcnt lgkmcnt(12)
	v_mfma_f32_32x32x16_bf16 v[2:17], v[28:31], v[60:63], v[2:17]
	s_waitcnt lgkmcnt(10)
	v_mfma_f32_32x32x16_bf16 v[2:17], v[32:35], v[80:83], v[2:17]
	s_waitcnt lgkmcnt(8)
	v_mfma_f32_32x32x16_bf16 v[2:17], v[36:39], v[84:87], v[2:17]
	s_waitcnt lgkmcnt(6)
	v_mfma_f32_32x32x16_bf16 v[2:17], v[40:43], v[88:91], v[2:17]
	s_waitcnt lgkmcnt(4)
	v_mfma_f32_32x32x16_bf16 v[2:17], v[44:47], v[92:95], v[2:17]
	s_waitcnt lgkmcnt(2)
	v_mfma_f32_32x32x16_bf16 v[2:17], v[48:51], v[96:99], v[2:17]
	s_waitcnt lgkmcnt(0)
	v_mfma_f32_32x32x16_bf16 v[2:17], v[52:55], v[100:103], v[2:17]
	s_waitcnt vmcnt(15)
	ds_write2_b64 v236, v[104:105], v[106:107] offset0:0 offset1:1
	s_waitcnt vmcnt(14)
	ds_write2_b64 v236, v[108:109], v[110:111] offset0:33 offset1:34
	s_waitcnt vmcnt(13)
	ds_write2_b64 v236, v[112:113], v[114:115] offset0:66 offset1:67
	s_waitcnt vmcnt(12)
	ds_write2_b64 v236, v[116:117], v[118:119] offset0:99 offset1:100
	s_waitcnt vmcnt(11)
	ds_write2_b64 v236, v[120:121], v[122:123] offset0:132 offset1:133
	s_waitcnt vmcnt(10)
	ds_write2_b64 v236, v[124:125], v[126:127] offset0:165 offset1:166
	s_waitcnt vmcnt(9)
	ds_write2_b64 v236, v[128:129], v[130:131] offset0:198 offset1:199
	s_waitcnt vmcnt(8)
	ds_write2_b64 v236, v[132:133], v[134:135] offset0:231 offset1:232
	s_waitcnt vmcnt(7)
	ds_write2_b64 v237, v[136:137], v[138:139] offset0:0 offset1:1
	s_waitcnt vmcnt(6)
	ds_write2_b64 v237, v[140:141], v[142:143] offset0:33 offset1:34
	s_waitcnt vmcnt(5)
	ds_write2_b64 v237, v[144:145], v[146:147] offset0:66 offset1:67
	s_waitcnt vmcnt(4)
	ds_write2_b64 v237, v[148:149], v[150:151] offset0:99 offset1:100
	s_waitcnt vmcnt(3)
	ds_write2_b64 v237, v[152:153], v[154:155] offset0:132 offset1:133
	s_waitcnt vmcnt(2)
	ds_write2_b64 v237, v[156:157], v[158:159] offset0:165 offset1:166
	s_waitcnt vmcnt(1)
	ds_write2_b64 v237, v[160:161], v[162:163] offset0:198 offset1:199
	s_waitcnt vmcnt(0)
	ds_write2_b64 v237, v[164:165], v[166:167] offset0:231 offset1:232
	s_waitcnt lgkmcnt(0)
	ds_read2_b64 v[104:107], v238 offset0:0 offset1:1
	ds_read2_b64 v[136:139], v239 offset0:0 offset1:1
	ds_read2_b64 v[108:111], v238 offset0:4 offset1:5
	ds_read2_b64 v[140:143], v239 offset0:4 offset1:5
	ds_read2_b64 v[112:115], v238 offset0:8 offset1:9
	ds_read2_b64 v[144:147], v239 offset0:8 offset1:9
	ds_read2_b64 v[116:119], v238 offset0:12 offset1:13
	ds_read2_b64 v[148:151], v239 offset0:12 offset1:13
	ds_read2_b64 v[120:123], v238 offset0:16 offset1:17
	ds_read2_b64 v[152:155], v239 offset0:16 offset1:17
	ds_read2_b64 v[124:127], v238 offset0:20 offset1:21
	ds_read2_b64 v[156:159], v239 offset0:20 offset1:21
	ds_read2_b64 v[128:131], v238 offset0:24 offset1:25
	ds_read2_b64 v[160:163], v239 offset0:24 offset1:25
	s_waitcnt lgkmcnt(12)
	v_mfma_f32_32x32x16_bf16 v[2:17], v[104:107], v[136:139], v[2:17]
	ds_read2_b64 v[132:135], v238 offset0:28 offset1:29
	ds_read2_b64 v[164:167], v239 offset0:28 offset1:29
	s_waitcnt lgkmcnt(12)
	v_mfma_f32_32x32x16_bf16 v[2:17], v[108:111], v[140:143], v[2:17]
	s_waitcnt lgkmcnt(10)
	v_mfma_f32_32x32x16_bf16 v[2:17], v[112:115], v[144:147], v[2:17]
	s_waitcnt lgkmcnt(8)
	v_mfma_f32_32x32x16_bf16 v[2:17], v[116:119], v[148:151], v[2:17]
	s_waitcnt lgkmcnt(6)
	v_mfma_f32_32x32x16_bf16 v[2:17], v[120:123], v[152:155], v[2:17]
	s_waitcnt lgkmcnt(4)
	v_mfma_f32_32x32x16_bf16 v[2:17], v[124:127], v[156:159], v[2:17]
	s_waitcnt lgkmcnt(2)
	v_mfma_f32_32x32x16_bf16 v[2:17], v[128:131], v[160:163], v[2:17]
	s_waitcnt lgkmcnt(0)
	v_mfma_f32_32x32x16_bf16 v[2:17], v[132:135], v[164:167], v[2:17]
	s_movk_i32 s4, 0x60
	v_and_or_b32 v21, v225, s4, v71
	v_sub_u32_e32 v24, v21, v183
	v_mul_f32_e32 v20, 0xbfb8aa3b, v19
	v_cmp_gt_i32_e64 s[4:5], 1, v24
	s_and_saveexec_b64 s[10:11], s[4:5]
	s_xor_b64 s[70:71], exec, s[10:11]
	s_cbranch_execz .LBB0_390
	v_sub_u32_e32 v19, 0, v24
	v_cvt_f32_u32_e32 v19, v19
	v_cmp_ne_u32_e64 s[4:5], v21, v183
	v_mul_f32_e32 v19, v20, v19
	v_exp_f32_e32 v19, v19
	s_nop 0
	v_cndmask_b32_e64 v19, 2.0, v19, s[4:5]
